# attention: cross-row max via v_permlane16/32_swap instead of LDS-routed ds_bpermute
# speedup vs baseline: 1.0606x; 1.0010x over previous
; #define LAS __attribute__((address_space(3)))
; DI unsigned cvtpk(float lo, float hi) { const f32x2 v = (f32x2){lo, hi}; const bf16x2_t b = __builtin_convertvector(v, bf16x2_t); return __builtin_bit_cast(unsigned, b); }
; DI void attn_phase(const PZ& p, LAS unsigned char* lds, int tid, int wave, int lane) {
;     ...
;             for (int mt = 0; mt < 2; ++mt) {
;                 float mx = sacc[0][mt][0];
; #pragma unroll
;                 for (int nt = 0; nt < 4; ++nt)
; #pragma unroll
;                     for (int j = 0; j < 4; ++j) mx = fmaxf(mx, sacc[nt][mt][j]);
;                 mx = fmaxf(mx, __shfl_xor(mx, 16)); mx = fmaxf(mx, __shfl_xor(mx, 32));
;                 const float mnew = fmaxf(mrow[mt], mx);
;                 const float alpha = __builtin_amdgcn_exp2f(mrow[mt] - mnew);
;                 mrow[mt] = mnew;
;                 float ls = lrow[mt] * alpha;
; #pragma unroll
;                 for (int nt = 0; nt < 4; ++nt)
; #pragma unroll
;                     for (int j = 0; j < 4; ++j) { const float pe = __builtin_amdgcn_exp2f(sacc[nt][mt][j] - mnew); sacc[nt][mt][j] = pe; ls += pe; }
;                 lrow[mt] = ls;
; #pragma unroll
;                 for (int md = 0; md < 4; ++md) oacc[md][mt] *= alpha;
;             }
; #pragma unroll
;             for (int kp = 0; kp < 2; ++kp) {
;                 bf16x8 pB[2];
; #pragma unroll
;                 for (int mt = 0; mt < 2; ++mt) {
;                     const f32x4 x0 = sacc[2 * kp][mt], x1 = sacc[2 * kp + 1][mt];
;                     pB[mt] = mk8((u32x2){cvtpk(x0.x, x0.y), cvtpk(x0.z, x0.w)}, (u32x2){cvtpk(x1.x, x1.y), cvtpk(x1.z, x1.w)});
;                 }
; #pragma unroll
;                 for (int md = 0; md < 4; ++md) {
;                     const bf16x8 vA = mk8(*(const LAS u32x2*)(Vs + (md * 16 + l15) * 72 + (2 * kp) * 16 + g * 4), *(const LAS u32x2*)(Vs + (md * 16 + l15) * 72 + (2 * kp + 1) * 16 + g * 4));
; #pragma unroll
;                     for (int mt = 0; mt < 2; ++mt) oacc[md][mt] = MFMA16(vA, pB[mt], oacc[md][mt]);
;                 }
;             }
;             if (it + 1 < ntiles) {
;                 *(LAS u32x4*)(KsB + ((it + 1) & 1) * (64 * 72) + rowi * 72 + piece * 8) = kreg;
;                 *(LAS u32x4*)(VsB + ((it + 1) & 1) * (64 * 72) + rowi * 72 + piece * 8) = vreg;
;             }
.LBB0_136:
	v_max_f32_e32 v112, v89, v89
	v_max_f32_e32 v113, v88, v88
	v_max_f32_e32 v112, v113, v112
	v_max3_f32 v112, v112, v90, v91
	v_max3_f32 v112, v112, v80, v81
	v_max3_f32 v112, v112, v82, v83
	v_max3_f32 v112, v112, v76, v77
	v_max3_f32 v112, v112, v78, v79
	v_max3_f32 v112, v112, v84, v85
	v_max3_f32 v112, v112, v86, v87
	v_mov_b32_e32 v113, v112
	s_lshl_b32 s8, s8, 1
	s_add_i32 s8, s8, 0
	s_andn2_b64 vcc, exec, s[24:25]
	s_waitcnt lgkmcnt(0)
	v_permlane16_swap_b32_e32 v112, v113
	v_max_f32_e32 v112, v112, v113
	v_mov_b32_e32 v113, v112
	s_nop 1
	v_permlane32_swap_b32_e32 v112, v113
	s_waitcnt lgkmcnt(0)
	v_max3_f32 v142, v110, v112, v113
	v_sub_f32_e32 v76, v76, v142
	v_exp_f32_e32 v120, v76
	v_sub_f32_e32 v76, v77, v142
	v_exp_f32_e32 v118, v76
	v_sub_f32_e32 v76, v78, v142
	v_sub_f32_e32 v110, v110, v142
	v_exp_f32_e32 v116, v76
	v_sub_f32_e32 v76, v79, v142
	v_exp_f32_e32 v110, v110
	v_sub_f32_e32 v89, v89, v142
	v_sub_f32_e32 v80, v80, v142
	v_exp_f32_e32 v114, v76
	v_sub_f32_e32 v76, v84, v142
	v_exp_f32_e32 v112, v89
	v_sub_f32_e32 v89, v90, v142
	v_exp_f32_e32 v128, v80
	v_sub_f32_e32 v80, v81, v142
	v_exp_f32_e32 v90, v76
	v_sub_f32_e32 v76, v85, v142
	v_exp_f32_e32 v126, v80
	v_sub_f32_e32 v80, v82, v142
	v_exp_f32_e32 v84, v76
	v_sub_f32_e32 v76, v86, v142
	v_exp_f32_e32 v124, v80
	v_sub_f32_e32 v80, v83, v142
	v_exp_f32_e32 v82, v76
	v_sub_f32_e32 v76, v87, v142
	v_exp_f32_e32 v122, v80
	v_exp_f32_e32 v80, v76
	v_pk_mul_f32 v[76:77], v[52:53], v[110:111] op_sel_hi:[1,0]
	v_pk_mul_f32 v[52:53], v[44:45], v[110:111] op_sel_hi:[1,0]
	v_pk_mul_f32 v[44:45], v[48:49], v[110:111] op_sel_hi:[1,0]
	v_max_f32_e32 v48, v69, v69
	v_max_f32_e32 v49, v68, v68
	v_max_f32_e32 v48, v49, v48
	v_max3_f32 v48, v48, v70, v71
	v_max3_f32 v48, v48, v60, v61
	v_max3_f32 v48, v48, v62, v63
	v_max3_f32 v48, v48, v64, v65
	v_max3_f32 v48, v48, v66, v67
	v_max3_f32 v48, v48, v72, v73
	v_max3_f32 v48, v48, v74, v75
	v_mov_b32_e32 v49, v48
	v_exp_f32_e32 v132, v89
	v_sub_f32_e32 v89, v91, v142
	v_exp_f32_e32 v130, v89
	v_pk_mul_f32 v[78:79], v[54:55], v[110:111] op_sel_hi:[1,0]
	s_waitcnt lgkmcnt(0)
	v_permlane16_swap_b32_e32 v48, v49
	v_max_f32_e32 v48, v48, v49
	v_mov_b32_e32 v49, v48
	v_pk_mul_f32 v[58:59], v[58:59], v[110:111] op_sel_hi:[1,0]
	v_pk_mul_f32 v[56:57], v[56:57], v[110:111] op_sel_hi:[1,0]
	v_pk_mul_f32 v[54:55], v[46:47], v[110:111] op_sel_hi:[1,0]
	v_pk_mul_f32 v[46:47], v[50:51], v[110:111] op_sel_hi:[1,0]
	s_waitcnt lgkmcnt(0)
	v_permlane32_swap_b32_e32 v48, v49
	v_max3_f32 v87, v111, v48, v49
	v_sub_f32_e32 v48, v111, v87
	v_exp_f32_e32 v86, v48
	v_sub_f32_e32 v48, v68, v87
	v_exp_f32_e32 v89, v48
	v_sub_f32_e32 v48, v69, v87
	v_exp_f32_e32 v113, v48
	v_sub_f32_e32 v48, v70, v87
	v_exp_f32_e32 v133, v48
	v_sub_f32_e32 v48, v71, v87
	v_exp_f32_e32 v131, v48
	v_sub_f32_e32 v48, v60, v87
	v_exp_f32_e32 v129, v48
	v_sub_f32_e32 v48, v61, v87
	v_exp_f32_e32 v127, v48
	v_sub_f32_e32 v48, v62, v87
	v_exp_f32_e32 v125, v48
	v_sub_f32_e32 v48, v63, v87
	v_exp_f32_e32 v123, v48
	v_sub_f32_e32 v48, v64, v87
	v_exp_f32_e32 v121, v48
	v_sub_f32_e32 v48, v65, v87
	v_exp_f32_e32 v119, v48
	v_sub_f32_e32 v48, v66, v87
	v_exp_f32_e32 v117, v48
	v_sub_f32_e32 v48, v67, v87
	v_lshlrev_b32_e32 v111, 1, v135
	v_exp_f32_e32 v115, v48
	v_sub_f32_e32 v48, v72, v87
	v_add3_u32 v72, s8, v138, v111
	v_add_u32_e32 v143, 0x4800, v72
	ds_read2_b64 v[68:71], v143 offset1:4
	v_sub_f32_e32 v88, v88, v142
	v_exp_f32_e32 v88, v88
	v_exp_f32_e32 v91, v48
	v_sub_f32_e32 v48, v73, v87
	v_exp_f32_e32 v85, v48
	v_sub_f32_e32 v48, v74, v87
	v_exp_f32_e32 v83, v48
	v_sub_f32_e32 v48, v75, v87
	v_pk_mul_f32 v[42:43], v[42:43], v[86:87] op_sel_hi:[1,0]
	v_pk_mul_f32 v[40:41], v[40:41], v[86:87] op_sel_hi:[1,0]
	v_pk_mul_f32 v[62:63], v[38:39], v[86:87] op_sel_hi:[1,0]
	v_pk_mul_f32 v[60:61], v[36:37], v[86:87] op_sel_hi:[1,0]
	v_pk_mul_f32 v[66:67], v[34:35], v[86:87] op_sel_hi:[1,0]
	v_pk_mul_f32 v[64:65], v[32:33], v[86:87] op_sel_hi:[1,0]
	v_cvt_pk_bf16_f32 v32, v88, v112
	v_cvt_pk_bf16_f32 v33, v132, v130
	v_cvt_pk_bf16_f32 v34, v128, v126
	v_cvt_pk_bf16_f32 v35, v124, v122
	v_cvt_pk_bf16_f32 v36, v89, v113
	v_cvt_pk_bf16_f32 v37, v133, v131
	v_cvt_pk_bf16_f32 v38, v129, v127
	v_cvt_pk_bf16_f32 v39, v125, v123
	v_add_u32_e32 v148, 0x5000, v72
	v_exp_f32_e32 v81, v48
	s_waitcnt lgkmcnt(0)
	v_mfma_f32_16x16x32_bf16 v[48:51], v[68:71], v[32:35], v[76:79]
	v_add_u32_e32 v149, 0x5800, v72
	v_pk_mul_f32 v[30:31], v[30:31], v[86:87] op_sel_hi:[1,0]
	v_pk_mul_f32 v[28:29], v[28:29], v[86:87] op_sel_hi:[1,0]
	v_mfma_f32_16x16x32_bf16 v[40:43], v[68:71], v[36:39], v[40:43]
	ds_read2_b64 v[68:71], v148 offset0:32 offset1:36
	v_cvt_pk_bf16_f32 v76, v120, v118
	v_cvt_pk_bf16_f32 v77, v116, v114
	s_waitcnt lgkmcnt(0)
	v_mfma_f32_16x16x32_bf16 v[56:59], v[68:71], v[32:35], v[56:59]
	v_cvt_pk_bf16_f32 v78, v90, v84
	v_cvt_pk_bf16_f32 v79, v82, v80
	v_cvt_pk_bf16_f32 v144, v121, v119
	v_mfma_f32_16x16x32_bf16 v[60:63], v[68:71], v[36:39], v[60:63]
	ds_read2_b64 v[68:71], v149 offset0:64 offset1:68
	v_cvt_pk_bf16_f32 v145, v117, v115
	v_cvt_pk_bf16_f32 v146, v91, v85
	s_waitcnt lgkmcnt(0)
	v_mfma_f32_16x16x32_bf16 v[72:75], v[68:71], v[32:35], v[52:55]
	s_nop 2
	v_add3_u32 v52, s8, v139, v111
	v_add_u32_e32 v111, 0x4800, v52
	ds_read2_b64 v[52:55], v111 offset1:4
	v_mfma_f32_16x16x32_bf16 v[64:67], v[68:71], v[36:39], v[64:67]
	v_cvt_pk_bf16_f32 v147, v83, v81
	s_waitcnt lgkmcnt(0)
	v_mfma_f32_16x16x32_bf16 v[68:71], v[52:55], v[32:35], v[44:47]
	ds_read2_b64 v[32:35], v143 offset0:8 offset1:12
	v_mfma_f32_16x16x32_bf16 v[28:31], v[52:55], v[36:39], v[28:31]
	s_waitcnt lgkmcnt(0)
	v_mfma_f32_16x16x32_bf16 v[52:55], v[32:35], v[76:79], v[48:51]
	v_mfma_f32_16x16x32_bf16 v[40:43], v[32:35], v[144:147], v[40:43]
	ds_read2_b64 v[32:35], v148 offset0:40 offset1:44
	s_waitcnt lgkmcnt(0)
	v_mfma_f32_16x16x32_bf16 v[56:59], v[32:35], v[76:79], v[56:59]
	v_mfma_f32_16x16x32_bf16 v[36:39], v[32:35], v[144:147], v[60:63]
	ds_read2_b64 v[32:35], v149 offset0:72 offset1:76
	s_nop 1
	ds_read2_b64 v[60:63], v111 offset0:8 offset1:12
	s_waitcnt lgkmcnt(1)
	v_mfma_f32_16x16x32_bf16 v[44:47], v[32:35], v[76:79], v[72:75]
	v_mfma_f32_16x16x32_bf16 v[32:35], v[32:35], v[144:147], v[64:67]
	s_waitcnt lgkmcnt(0)
	v_mfma_f32_16x16x32_bf16 v[48:51], v[60:63], v[76:79], v[68:71]
	v_mfma_f32_16x16x32_bf16 v[28:31], v[60:63], v[144:147], v[28:31]
	s_cbranch_vccnz .LBB0_138
	s_bitcmp1_b32 s7, 0
	s_cselect_b32 s8, 0x2400, 0
	v_add_u32_e32 v60, s8, v95
	s_waitcnt vmcnt(1)
	ds_write_b128 v60, v[20:23]
	s_waitcnt vmcnt(0)
	ds_write_b128 v60, v[24:27] offset:18432
